# L2 warm-up of the w_in transpose source tiles before each workgroup's pass-B item list (one line touch per thread per tile, hidden behind the kc item)
# baseline (speedup 1.0000x reference)
.LBB0_156:
	s_or_b64 exec, exec, s[0:1]
	s_mov_b32 s100, 0x3e0
	s_add_u32 s99, s81, 0x100
	s_cmp_lt_u32 s81, 0x60
	s_cselect_b32 s99, s99, s81
	s_and_b32 vcc_lo, s81, 8
	s_cmp_eq_u32 vcc_lo, 0
	s_cbranch_scc1 .Lgrp_a
	v_readlane_b32 s2, v240, 5
	v_readlane_b32 s3, v240, 6
	v_lshrrev_b32_e32 v242, 8, v193
	v_bfe_u32 v243, v193, 2, 6
	v_bfe_u32 v247, v193, 1, 1
	v_lshlrev_b32_e32 v247, 7, v247
	s_add_i32 s4, s81, 0x200
	s_lshl_b32 s5, s4, 1
	s_sub_i32 s5, s5, 0x2c0
	v_add_u32_e32 v244, s5, v242
	v_mul_u32_u24_e32 v245, 0xcccd, v244
	v_lshrrev_b32_e32 v245, 22, v245
	v_mul_u32_u24_e32 v246, 0x50, v245
	v_sub_u32_e32 v246, v244, v246
	v_lshl_add_u32 v245, v245, 6, v243
	v_mul_u32_u24_e32 v245, 0x5000, v245
	v_lshl_add_u32 v245, v246, 8, v245
	v_add_u32_e32 v245, v245, v247
	global_load_dword v248, v245, s[2:3]
	s_cmpk_ge_i32 s81, 0xe0
	s_cbranch_scc1 .Lpf_b1
	s_add_i32 s4, s81, 0x300
	s_lshl_b32 s5, s4, 1
	s_sub_i32 s5, s5, 0x2c0
	v_add_u32_e32 v244, s5, v242
	v_mul_u32_u24_e32 v245, 0xcccd, v244
	v_lshrrev_b32_e32 v245, 22, v245
	v_mul_u32_u24_e32 v246, 0x50, v245
	v_sub_u32_e32 v246, v244, v246
	v_lshl_add_u32 v245, v245, 6, v243
	v_mul_u32_u24_e32 v245, 0x5000, v245
	v_lshl_add_u32 v245, v246, 8, v245
	v_add_u32_e32 v245, v245, v247
	global_load_dword v249, v245, s[2:3]
.Lpf_b1:
	s_cmpk_lt_i32 s81, 0x60
	s_cbranch_scc1 .Lpf_b2
	s_add_i32 s4, s81, 0x100
	s_lshl_b32 s5, s4, 1
	s_sub_i32 s5, s5, 0x2c0
	v_add_u32_e32 v244, s5, v242
	v_mul_u32_u24_e32 v245, 0xcccd, v244
	v_lshrrev_b32_e32 v245, 22, v245
	v_mul_u32_u24_e32 v246, 0x50, v245
	v_sub_u32_e32 v246, v244, v246
	v_lshl_add_u32 v245, v245, 6, v243
	v_mul_u32_u24_e32 v245, 0x5000, v245
	v_lshl_add_u32 v245, v246, 8, v245
	v_add_u32_e32 v245, v245, v247
	global_load_dword v251, v245, s[2:3]
.Lpf_b2:
	s_mov_b32 s101, 2
	s_sub_u32 s0, s78, 0x160
	s_subb_u32 s1, s79, 0
	s_branch .Lp0_enter

.LBB0_179:
	s_cmp_eq_u32 s101, 1
	s_cbranch_scc0 .Lst_gs2
	v_readlane_b32 s2, v240, 5
	v_readlane_b32 s3, v240, 6
	v_lshrrev_b32_e32 v242, 8, v193
	v_bfe_u32 v243, v193, 2, 6
	v_bfe_u32 v247, v193, 1, 1
	v_lshlrev_b32_e32 v247, 7, v247
	s_add_i32 s4, s81, 0x200
	s_lshl_b32 s5, s4, 1
	s_sub_i32 s5, s5, 0x2c0
	v_add_u32_e32 v244, s5, v242
	v_mul_u32_u24_e32 v245, 0xcccd, v244
	v_lshrrev_b32_e32 v245, 22, v245
	v_mul_u32_u24_e32 v246, 0x50, v245
	v_sub_u32_e32 v246, v244, v246
	v_lshl_add_u32 v245, v245, 6, v243
	v_mul_u32_u24_e32 v245, 0x5000, v245
	v_lshl_add_u32 v245, v246, 8, v245
	v_add_u32_e32 v245, v245, v247
	global_load_dword v248, v245, s[2:3]
	s_cmpk_ge_i32 s81, 0xe0
	s_cbranch_scc1 .Lpf_a1
	s_add_i32 s4, s81, 0x300
	s_lshl_b32 s5, s4, 1
	s_sub_i32 s5, s5, 0x2c0
	v_add_u32_e32 v244, s5, v242
	v_mul_u32_u24_e32 v245, 0xcccd, v244
	v_lshrrev_b32_e32 v245, 22, v245
	v_mul_u32_u24_e32 v246, 0x50, v245
	v_sub_u32_e32 v246, v244, v246
	v_lshl_add_u32 v245, v245, 6, v243
	v_mul_u32_u24_e32 v245, 0x5000, v245
	v_lshl_add_u32 v245, v246, 8, v245
	v_add_u32_e32 v245, v245, v247
	global_load_dword v249, v245, s[2:3]

.Lpf_a2:
	s_mov_b32 s101, 4
	s_sub_u32 s0, s78, 0x160
	s_subb_u32 s1, s79, 0
	s_branch .Lp0_enter
